# final: per-panel seams 2/3 + L2-shared granule exchange + XCC co-location check with fallbacks; poll bounds raised to the baseline's spin caps
# speedup vs baseline: 1.0002x; 1.0002x over previous
; __device__ __forceinline__ int lane_id() { int l; asm volatile("v_mbcnt_lo_u32_b32 %0, -1, 0\n\tv_mbcnt_hi_u32_b32 %0, -1, %0" : "=v"(l)); return l; }
; __device__ __forceinline__ void xcd_barrier(const XcdBarrier& b) {
;     asm volatile("s_waitcnt vmcnt(0)" ::: "memory");
;     __syncthreads();
;     if (b.w0 != 0 && lane_id() == 0) {
.LBB0_99:
	v_mbcnt_lo_u32_b32 v0, -1, 0
	v_mbcnt_hi_u32_b32 v0, -1, v0
	v_readlane_b32 s99, v254, 25
	s_and_b32 s99, s99, 0xffffffc7
	v_lshlrev_b32_e32 v0, 3, v0
	v_and_b32_e32 v0, 56, v0
	v_or_b32_e32 v0, s99, v0
	v_lshlrev_b32_e32 v0, 2, v0
	s_add_u32 s100, s34, 0x1c800
	s_addc_u32 s101, s35, 0
	global_load_dword v1, v0, s[100:101] sc1
	s_waitcnt vmcnt(0)
	s_mov_b32 s99, 0x20000

; __device__ __forceinline__ int lane_id() { int l; asm volatile("v_mbcnt_lo_u32_b32 %0, -1, 0\n\tv_mbcnt_hi_u32_b32 %0, -1, %0" : "=v"(l)); return l; }
; __device__ __forceinline__ unsigned xb_ld(unsigned* p)              { return __hip_atomic_load(p, __ATOMIC_RELAXED, __HIP_MEMORY_SCOPE_AGENT); }
; #define XB_SPIN(cond, bar) do { unsigned _sp = 0; while (cond) { __builtin_amdgcn_s_sleep(1); \
;     if ((++_sp & 255u) == 0u) { if (xb_ld(&(bar)[XB_TMO])) break; if (_sp > XB_SPIN_CAP) { atomicAdd(&(bar)[XB_TMO], 1u); break; } } } } while (0)
; __device__ __forceinline__ void xcd_wait2(const XcdBarrier& b, unsigned use, unsigned* obar, unsigned ouse) {
;     if (b.w0 != 0 && lane_id() == 0) {
;         unsigned* bar = b.bar;
;         XB_SPIN(xb_ld(&obar[XB_TOPGEN]) <= ouse, bar);
;         XB_SPIN(xb_ld(&bar[XB_TOPGEN]) <= use, bar);
;         __builtin_amdgcn_fence(__ATOMIC_ACQUIRE, "agent");
;         asm volatile("s_waitcnt vmcnt(0)" ::: "memory");
;     }
;     __syncthreads();
.LBB0_501:
	v_readlane_b32 s38, v254, 19
	v_readlane_b32 s39, v254, 21
	s_add_i32 s38, s38, s39
	s_lshl_b32 s38, s38, 7
	s_add_u32 s38, s38, 0x7000
	v_mov_b32_e32 v0, s38
	s_mov_b32 s0, 0x40000

; __device__ __forceinline__ u32x4 pack8(const f32x4 a, const f32x4 b) { u32x4 w; w.x = cvt_pk_bf16(a[0], a[1]); w.y = cvt_pk_bf16(a[2], a[3]); w.z = cvt_pk_bf16(b[0], b[1]); w.w = cvt_pk_bf16(b[2], b[3]); return w; }
; __device__ __forceinline__ int lane_id() { int l; asm volatile("v_mbcnt_lo_u32_b32 %0, -1, 0\n\tv_mbcnt_hi_u32_b32 %0, -1, %0" : "=v"(l)); return l; }
; __device__ __forceinline__ unsigned xb_ld(unsigned* p)              { return __hip_atomic_load(p, __ATOMIC_RELAXED, __HIP_MEMORY_SCOPE_AGENT); }
; #define XB_SPIN(cond, bar) do { unsigned _sp = 0; while (cond) { __builtin_amdgcn_s_sleep(1); \
;     if ((++_sp & 255u) == 0u) { if (xb_ld(&(bar)[XB_TMO])) break; if (_sp > XB_SPIN_CAP) { atomicAdd(&(bar)[XB_TMO], 1u); break; } } } } while (0)
;     __device__ __forceinline__ void operator()(const f32x4 (&acc)[2][2][4][2], const Unit& u, int wr, int wc, int fr, int fq) const {
;         const int row0 = u.pm * BM + wr * 64 + fr, col0 = u.pn * BM + wc * 32 + 8 * fq;
; #pragma unroll
;         for (int ai = 0; ai < 2; ++ai)
; #pragma unroll
;             for (int m = 0; m < 4; ++m) { bf16_t* rowp = O + (size_t)(row0 + ai * HALF + m * 16) * ldc + col0;
; #pragma unroll
;                 for (int bj = 0; bj < 2; ++bj) *(u32x4*)(rowp + bj * HALF) = pack8(acc[ai][bj][m][0], acc[ai][bj][m][1]); }
; __device__ __forceinline__ void xcd_wait(const XcdBarrier& b, unsigned use) {
;     if (b.w0 != 0 && lane_id() == 0) {
;         unsigned* bar = b.bar;
;         XB_SPIN(xb_ld(&bar[XB_TOPGEN]) <= use, bar);
;         __builtin_amdgcn_fence(__ATOMIC_ACQUIRE, "agent");
;         asm volatile("s_waitcnt vmcnt(0)" ::: "memory");
;     }
;     __syncthreads();
.LBB0_558:
	v_lshl_add_u32 v130, s6, 8, v128
	v_ashrrev_i32_e32 v131, 31, v130
	v_or_b32_e32 v132, s97, v129
	v_lshlrev_b64 v[128:129], 12, v[130:131]
	v_lshl_add_u64 v[128:129], s[2:3], 0, v[128:129]
	v_lshlrev_b32_e32 v224, 1, v132
	v_mov_b32_e32 v225, 0
	v_lshl_add_u64 v[128:129], v[128:129], 0, v[224:225]
	v_cvt_pk_bf16_f32 v120, v120, v121
	v_cvt_pk_bf16_f32 v121, v122, v123
	v_cvt_pk_bf16_f32 v122, v112, v113
	v_cvt_pk_bf16_f32 v123, v114, v115
	global_store_dwordx4 v[128:129], v[120:123], off
	v_cvt_pk_bf16_f32 v112, v124, v125
	v_cvt_pk_bf16_f32 v113, v126, v127
	v_cvt_pk_bf16_f32 v114, v116, v117
	v_cvt_pk_bf16_f32 v115, v118, v119
	global_store_dwordx4 v[128:129], v[112:115], off offset:256
	v_cvt_pk_bf16_f32 v104, v104, v105
	v_cvt_pk_bf16_f32 v105, v106, v107
	v_cvt_pk_bf16_f32 v106, v96, v97
	v_cvt_pk_bf16_f32 v107, v98, v99
	s_mov_b64 s[0:1], 0x80000
	s_nop 0
	v_or_b32_e32 v112, 16, v130
	v_ashrrev_i32_e32 v113, 31, v112
	v_lshlrev_b64 v[112:113], 12, v[112:113]
	v_lshl_add_u64 v[112:113], s[2:3], 0, v[112:113]
	v_lshl_add_u64 v[112:113], v[112:113], 0, v[224:225]
	global_store_dwordx4 v[112:113], v[104:107], off
	v_cvt_pk_bf16_f32 v96, v108, v109
	v_cvt_pk_bf16_f32 v97, v110, v111
	v_cvt_pk_bf16_f32 v98, v100, v101
	v_cvt_pk_bf16_f32 v99, v102, v103
	global_store_dwordx4 v[112:113], v[96:99], off offset:256
	v_cvt_pk_bf16_f32 v88, v88, v89
	v_cvt_pk_bf16_f32 v89, v90, v91
	v_cvt_pk_bf16_f32 v90, v80, v81
	v_cvt_pk_bf16_f32 v91, v82, v83
	s_mov_b32 s42, 0
	s_nop 0
	v_or_b32_e32 v96, 32, v130
	v_ashrrev_i32_e32 v97, 31, v96
	v_lshlrev_b64 v[96:97], 12, v[96:97]
	v_lshl_add_u64 v[96:97], s[2:3], 0, v[96:97]
	v_lshl_add_u64 v[96:97], v[96:97], 0, v[224:225]
	global_store_dwordx4 v[96:97], v[88:91], off
	v_cvt_pk_bf16_f32 v80, v92, v93
	v_cvt_pk_bf16_f32 v81, v94, v95
	v_cvt_pk_bf16_f32 v82, v84, v85
	v_cvt_pk_bf16_f32 v83, v86, v87
	global_store_dwordx4 v[96:97], v[80:83], off offset:256
	v_cvt_pk_bf16_f32 v56, v56, v57
	v_cvt_pk_bf16_f32 v57, v58, v59
	v_cvt_pk_bf16_f32 v58, v48, v49
	v_cvt_pk_bf16_f32 v59, v50, v51
	s_nop 1
	v_or_b32_e32 v80, 48, v130
	v_ashrrev_i32_e32 v81, 31, v80
	v_lshlrev_b64 v[80:81], 12, v[80:81]
	v_lshl_add_u64 v[80:81], s[2:3], 0, v[80:81]
	v_lshl_add_u64 v[80:81], v[80:81], 0, v[224:225]
	global_store_dwordx4 v[80:81], v[56:59], off
	v_cvt_pk_bf16_f32 v48, v60, v61
	v_cvt_pk_bf16_f32 v49, v62, v63
	v_cvt_pk_bf16_f32 v50, v52, v53
	v_lshl_add_u64 v[52:53], v[128:129], 0, s[0:1]
	s_mov_b32 s0, 0x80000
	v_cvt_pk_bf16_f32 v51, v54, v55
	v_add_co_u32_e32 v54, vcc, s0, v128
	global_store_dwordx4 v[80:81], v[48:51], off offset:256
	s_nop 0
	v_addc_co_u32_e32 v55, vcc, 0, v129, vcc
	v_cvt_pk_bf16_f32 v48, v76, v77
	v_cvt_pk_bf16_f32 v49, v78, v79
	v_cvt_pk_bf16_f32 v50, v72, v73
	v_cvt_pk_bf16_f32 v51, v74, v75
	global_store_dwordx4 v[54:55], v[48:51], off
	s_mov_b64 s[0:1], 0x90000
	s_nop 0
	v_cvt_pk_bf16_f32 v48, v68, v69
	v_cvt_pk_bf16_f32 v49, v70, v71
	v_cvt_pk_bf16_f32 v50, v64, v65
	v_cvt_pk_bf16_f32 v51, v66, v67
	global_store_dwordx4 v[52:53], v[48:51], off offset:256
	v_cvt_pk_bf16_f32 v44, v44, v45
	v_cvt_pk_bf16_f32 v45, v46, v47
	v_cvt_pk_bf16_f32 v46, v36, v37
	v_cvt_pk_bf16_f32 v47, v38, v39
	s_nop 1
	v_lshl_add_u64 v[48:49], v[128:129], 0, s[0:1]
	s_mov_b32 s0, 0x90000
	v_add_co_u32_e32 v36, vcc, s0, v128
	s_mov_b64 s[0:1], 0xa0000
	s_nop 0
	v_addc_co_u32_e32 v37, vcc, 0, v129, vcc
	global_store_dwordx4 v[36:37], v[44:47], off
	v_cvt_pk_bf16_f32 v36, v40, v41
	v_cvt_pk_bf16_f32 v37, v42, v43
	v_cvt_pk_bf16_f32 v38, v32, v33
	v_lshl_add_u64 v[32:33], v[128:129], 0, s[0:1]
	s_mov_b32 s0, 0xa0000
	v_cvt_pk_bf16_f32 v39, v34, v35
	global_store_dwordx4 v[48:49], v[36:39], off offset:256
	v_cvt_pk_bf16_f32 v28, v28, v29
	v_cvt_pk_bf16_f32 v29, v30, v31
	v_cvt_pk_bf16_f32 v30, v20, v21
	v_add_co_u32_e32 v20, vcc, s0, v128
	s_mov_b64 s[0:1], 0xb0000
	s_nop 0
	v_addc_co_u32_e32 v21, vcc, 0, v129, vcc
	v_cvt_pk_bf16_f32 v31, v22, v23
	global_store_dwordx4 v[20:21], v[28:31], off
	v_cvt_pk_bf16_f32 v20, v24, v25
	v_cvt_pk_bf16_f32 v21, v26, v27
	v_cvt_pk_bf16_f32 v22, v16, v17
	v_lshl_add_u64 v[16:17], v[128:129], 0, s[0:1]
	s_mov_b32 s0, 0xb0000
	v_cvt_pk_bf16_f32 v23, v18, v19
	global_store_dwordx4 v[32:33], v[20:23], off offset:256
	v_cvt_pk_bf16_f32 v12, v12, v13
	v_cvt_pk_bf16_f32 v13, v14, v15
	v_cvt_pk_bf16_f32 v14, v4, v5
	v_add_co_u32_e32 v4, vcc, s0, v128
	v_cvt_pk_bf16_f32 v15, v6, v7
	s_nop 1
	v_addc_co_u32_e32 v5, vcc, 0, v129, vcc
	global_store_dwordx4 v[4:5], v[12:15], off
	v_cvt_pk_bf16_f32 v4, v8, v9
	v_cvt_pk_bf16_f32 v5, v10, v11
	v_cvt_pk_bf16_f32 v6, v0, v1
	v_cvt_pk_bf16_f32 v7, v2, v3
	global_store_dwordx4 v[16:17], v[4:7], off offset:256
	s_waitcnt vmcnt(0)
	s_and_b64 vcc, exec, s[94:95]
	s_barrier
	s_cbranch_vccnz .LBB0_575
	v_mbcnt_lo_u32_b32 v0, -1, 0
	v_mbcnt_hi_u32_b32 v0, -1, v0
	s_nop 0
	v_cmp_eq_u32_e32 vcc, 0, v0
	s_and_saveexec_b64 s[0:1], vcc
	s_cbranch_execz .LBB0_574
	v_readlane_b32 s6, v254, 19
	v_readlane_b32 s7, v254, 21
	s_add_i32 s6, s6, s7
	s_lshl_b32 s6, s6, 7
	s_add_u32 s6, s6, 0x7800
	v_mov_b32_e32 v0, s6
	s_mov_b32 s13, 0x40000

;     __device__ __forceinline__ bool run(const f32x4 (&v)[2][2][4][2], const Unit& u, int wr, int wc, int fr, int fq, PG8_LAS unsigned char* lds, int wid, int lane) const {
;     ...
;         if (lane < 32) { const float tot = (P[row * 4 + 0] + P[row * 4 + 1]) + (P[row * 4 + 2] + P[row * 4 + 3]);
;             __hip_atomic_store(xbuf + ((size_t)(u.pm * BM + row) * 8 + u.pn), __float_as_uint(tot), __ATOMIC_RELAXED, __HIP_MEMORY_SCOPE_AGENT); }
;         asm volatile("s_waitcnt vmcnt(0)" ::: "memory");
;         if (lane == 0) __hip_atomic_fetch_add(cnt + 64 * u.pm, 1u, __ATOMIC_RELAXED, __HIP_MEMORY_SCOPE_AGENT);
;         if (wid == 0) {
;             bool dead = false; const unsigned long long t0 = __builtin_amdgcn_s_memrealtime();
;             for (;;) {
;                 if ((unsigned)__builtin_amdgcn_readfirstlane(__hip_atomic_load(cnt + 64 * u.pm, __ATOMIC_RELAXED, __HIP_MEMORY_SCOPE_AGENT)) >= 64u) break;
;                 if (__builtin_amdgcn_s_memrealtime() - t0 > 2000000ull) { if (lane == 0) __hip_atomic_store(tmo, 1u, __ATOMIC_RELAXED, __HIP_MEMORY_SCOPE_AGENT); dead = true; break; }
;                 __builtin_amdgcn_s_sleep(2);
;             }
;             if (lane == 0) flag[0] = dead ? 1u : 0u;
;         }
;         asm volatile("s_waitcnt vmcnt(0) lgkmcnt(0)" ::: "memory"); __builtin_amdgcn_s_barrier(); asm volatile("" ::: "memory");
;         const bool bad = flag[0] != 0u;
;         if (lane < 32) { const unsigned* slot = xbuf + (size_t)(u.pm * BM + row) * 8; float s = 0.f;
; #pragma unroll
;             for (int t = 0; t < 8; ++t) s += __uint_as_float(__hip_atomic_load(slot + t, __ATOMIC_RELAXED, __HIP_MEMORY_SCOPE_AGENT));
;             S[row] = 1.0f / sqrtf(s * (1.0f / 2048.0f) + 1e-6f); }
.LBB0_600:
	s_or_b64 exec, exec, s[0:1]
	s_waitcnt lgkmcnt(0)
	s_barrier
	s_waitcnt lgkmcnt(0)
	v_and_or_b32 v147, v249, 31, s65
	v_add_u32_e32 v144, s6, v147
	v_cmp_gt_u32_e64 s[0:1], 32, v146
	v_ashrrev_i32_e32 v145, 31, v144
	s_cmp_lg_u32 s98, 0
	s_cbranch_scc1 .Lgx_orig
	s_sub_u32 s6, s10, s34
	s_sub_u32 s6, s6, 0x2800000
	s_add_u32 s44, s10, s6
	s_addc_u32 s45, s11, 0
	s_add_u32 s44, s44, 0x100000
	s_addc_u32 s45, s45, 0
	s_sub_u32 s46, s22, s10
	s_lshl_b32 s46, s46, 1
	v_mov_b32_e32 v146, 0
	s_and_saveexec_b64 s[6:7], s[0:1]
	s_cbranch_execz .Lgx_end
	v_lshl_add_u32 v148, v147, 4, 0
	ds_read_b128 v[148:151], v148
	v_lshlrev_b32_e32 v159, 6, v144
	v_add_u32_e32 v160, s46, v159
	v_mov_b32_e32 v161, 0x13572468
	s_waitcnt lgkmcnt(0)
	v_mov_b32_e32 v154, v149
	v_mov_b32_e32 v155, v150
	v_mov_b32_e32 v149, v151
	v_pk_add_f32 v[148:149], v[154:155], v[148:149]
	s_nop 0
	v_pk_add_f32 v[148:149], v[148:149], v[148:149] op_sel:[0,1] op_sel_hi:[1,0]
	s_nop 0
	v_mov_b32_e32 v149, v161
	global_store_dwordx2 v160, v[148:149], s[44:45]
	s_mov_b32 s47, 0x40000
